# out-proj/MLP2 epilogue: X/gate loads of sub-blocks 2-4 issued before the LDS exchange barriers
# baseline (speedup 1.0000x reference)
.LBB0_1130:
	s_and_b64 vcc, exec, s[48:49]
	s_cbranch_vccnz .Lep1_2_skipld
	v_mov_b32_e32 v176, v110
	v_add_u32_e32 v178, 0xfffff000, v176
	v_lshrrev_b32_e32 v178, 11, v178
	v_mad_u32_u24 v178, v178, s33, s33
	v_cmp_lt_i32_e32 vcc, s94, v176
	v_ashrrev_i32_e32 v177, 31, v176
	v_mov_b32_e32 v179, 0
	v_cndmask_b32_e32 v178, 0, v178, vcc
	v_lshl_add_u64 v[180:181], v[178:179], 2, v[100:101]
	global_load_dwordx4 v[182:185], v[180:181], off offset:512
	v_lshlrev_b64 v[186:187], 13, v[176:177]
	v_lshl_add_u64 v[186:187], v[102:103], 0, v[186:187]
	s_mov_b32 s50, 0x20000
	s_mov_b32 s51, 0
	global_load_dwordx4 v[202:205], v[186:187], off offset:512
	v_lshl_add_u64 v[188:189], v[186:187], 0, s[50:51]
	global_load_dwordx4 v[206:209], v[188:189], off offset:512
	v_lshl_add_u64 v[190:191], v[188:189], 0, s[50:51]
	global_load_dwordx4 v[210:213], v[190:191], off offset:512
	v_lshl_add_u64 v[192:193], v[190:191], 0, s[50:51]
	global_load_dwordx4 v[214:217], v[192:193], off offset:512
	v_lshl_add_u64 v[194:195], v[192:193], 0, s[50:51]
	global_load_dwordx4 v[218:221], v[194:195], off offset:512
	v_lshl_add_u64 v[196:197], v[194:195], 0, s[50:51]
	global_load_dwordx4 v[222:225], v[196:197], off offset:512
	v_lshl_add_u64 v[198:199], v[196:197], 0, s[50:51]
	global_load_dwordx4 v[226:229], v[198:199], off offset:512
	v_lshl_add_u64 v[200:201], v[198:199], 0, s[50:51]
	global_load_dwordx4 v[230:233], v[200:201], off offset:512
.Lep1_2_skipld:
	s_waitcnt lgkmcnt(0)
	s_barrier
	ds_write2_b32 v165, v64, v80 offset1:16
	ds_write2_b32 v165, v65, v81 offset0:132 offset1:148
	ds_write2_b32 v116, v66, v82 offset0:8 offset1:24
	ds_write2_b32 v116, v67, v83 offset0:140 offset1:156
	ds_write2_b32 v117, v68, v84 offset0:64 offset1:80
	ds_write2_b32 v117, v69, v85 offset0:196 offset1:212
	ds_write2_b32 v112, v70, v86 offset0:72 offset1:88
	ds_write2_b32 v112, v71, v87 offset0:204 offset1:220
	ds_write2_b32 v113, v72, v88 offset0:128 offset1:144
	ds_write2_b32 v114, v73, v89 offset0:4 offset1:20
	ds_write2_b32 v114, v74, v90 offset0:136 offset1:152
	ds_write2_b32 v115, v75, v91 offset0:12 offset1:28
	ds_write2_b32 v111, v76, v92 offset0:192 offset1:208
	ds_write2_b32 v118, v77, v93 offset0:68 offset1:84
	ds_write2_b32 v118, v78, v94 offset0:200 offset1:216
	ds_write2_b32 v119, v79, v95 offset0:76 offset1:92
	v_or_b32_e32 v64, 0x80, v144
	v_ashrrev_i32_e32 v65, 31, v64
	v_lshlrev_b64 v[64:65], 2, v[64:65]
	v_lshl_add_u64 v[68:69], s[52:53], 0, v[64:65]
	v_lshl_add_u64 v[70:71], s[38:39], 0, v[64:65]
	v_lshl_add_u64 v[72:73], v[138:139], 0, s[56:57]
	s_mov_b32 s37, 0
	v_mov_b32_e32 v78, v135
	s_waitcnt lgkmcnt(0)
	s_barrier
	s_and_b64 vcc, exec, s[48:49]
	s_cbranch_vccnz .Lep1_2_part
	ds_read_b128 v[234:237], v135
	ds_read_b128 v[238:241], v135 offset:8448
	ds_read_b128 v[242:245], v135 offset:16896
	ds_read_b128 v[246:249], v135 offset:25344
	s_waitcnt vmcnt(7) lgkmcnt(3)
	v_pk_fma_f32 v[202:203], v[234:235], v[182:183], v[202:203]
	v_pk_fma_f32 v[204:205], v[236:237], v[184:185], v[204:205]
	global_store_dwordx4 v[186:187], v[202:205], off offset:512
	ds_read_b128 v[234:237], v135 offset:33792
	s_waitcnt vmcnt(7) lgkmcnt(3)
	v_pk_fma_f32 v[206:207], v[238:239], v[182:183], v[206:207]
	v_pk_fma_f32 v[208:209], v[240:241], v[184:185], v[208:209]
	global_store_dwordx4 v[188:189], v[206:209], off offset:512
	ds_read_b128 v[238:241], v135 offset:42240
	s_waitcnt vmcnt(7) lgkmcnt(3)
	v_pk_fma_f32 v[210:211], v[242:243], v[182:183], v[210:211]
	v_pk_fma_f32 v[212:213], v[244:245], v[184:185], v[212:213]
	global_store_dwordx4 v[190:191], v[210:213], off offset:512
	ds_read_b128 v[242:245], v135 offset:50688
	s_waitcnt vmcnt(7) lgkmcnt(3)
	v_pk_fma_f32 v[214:215], v[246:247], v[182:183], v[214:215]
	v_pk_fma_f32 v[216:217], v[248:249], v[184:185], v[216:217]
	global_store_dwordx4 v[192:193], v[214:217], off offset:512
	ds_read_b128 v[246:249], v135 offset:59136
	s_waitcnt vmcnt(7) lgkmcnt(3)
	v_pk_fma_f32 v[218:219], v[234:235], v[182:183], v[218:219]
	v_pk_fma_f32 v[220:221], v[236:237], v[184:185], v[220:221]
	global_store_dwordx4 v[194:195], v[218:221], off offset:512
	s_waitcnt vmcnt(7) lgkmcnt(2)
	v_pk_fma_f32 v[222:223], v[238:239], v[182:183], v[222:223]
	v_pk_fma_f32 v[224:225], v[240:241], v[184:185], v[224:225]
	global_store_dwordx4 v[196:197], v[222:225], off offset:512
	s_waitcnt vmcnt(7) lgkmcnt(1)
	v_pk_fma_f32 v[226:227], v[242:243], v[182:183], v[226:227]
	v_pk_fma_f32 v[228:229], v[244:245], v[184:185], v[228:229]
	global_store_dwordx4 v[198:199], v[226:229], off offset:512
	s_waitcnt vmcnt(7) lgkmcnt(0)
	v_pk_fma_f32 v[230:231], v[246:247], v[182:183], v[230:231]
	v_pk_fma_f32 v[232:233], v[248:249], v[184:185], v[232:233]
	global_store_dwordx4 v[200:201], v[230:233], off offset:512
	s_branch .Lep1_2_done

.Lep1_2_done:
.LBB0_1140:
	s_and_b64 vcc, exec, s[48:49]
	s_cbranch_vccnz .Lep1_3_skipld
	v_add_u32_e32 v176, 0x80, v110
	v_add_u32_e32 v178, 0xfffff000, v176
	v_lshrrev_b32_e32 v178, 11, v178
	v_mad_u32_u24 v178, v178, s33, s33
	v_cmp_lt_i32_e32 vcc, s94, v176
	v_ashrrev_i32_e32 v177, 31, v176
	v_mov_b32_e32 v179, 0
	v_cndmask_b32_e32 v178, 0, v178, vcc
	v_lshl_add_u64 v[180:181], v[178:179], 2, v[100:101]
	global_load_dwordx4 v[182:185], v[180:181], off
	v_lshlrev_b64 v[186:187], 13, v[176:177]
	v_lshl_add_u64 v[186:187], v[102:103], 0, v[186:187]
	s_mov_b32 s50, 0x20000
	s_mov_b32 s51, 0
	global_load_dwordx4 v[202:205], v[186:187], off
	v_lshl_add_u64 v[188:189], v[186:187], 0, s[50:51]
	global_load_dwordx4 v[206:209], v[188:189], off
	v_lshl_add_u64 v[190:191], v[188:189], 0, s[50:51]
	global_load_dwordx4 v[210:213], v[190:191], off
	v_lshl_add_u64 v[192:193], v[190:191], 0, s[50:51]
	global_load_dwordx4 v[214:217], v[192:193], off
	v_lshl_add_u64 v[194:195], v[192:193], 0, s[50:51]
	global_load_dwordx4 v[218:221], v[194:195], off
	v_lshl_add_u64 v[196:197], v[194:195], 0, s[50:51]
	global_load_dwordx4 v[222:225], v[196:197], off
	v_lshl_add_u64 v[198:199], v[196:197], 0, s[50:51]
	global_load_dwordx4 v[226:229], v[198:199], off
	v_lshl_add_u64 v[200:201], v[198:199], 0, s[50:51]
	global_load_dwordx4 v[230:233], v[200:201], off
.Lep1_3_skipld:
	s_waitcnt lgkmcnt(0)
	s_barrier
	ds_write2_b32 v165, v32, v48 offset1:16
	ds_write2_b32 v165, v33, v49 offset0:132 offset1:148
	ds_write2_b32 v116, v34, v50 offset0:8 offset1:24
	ds_write2_b32 v116, v35, v51 offset0:140 offset1:156
	ds_write2_b32 v117, v36, v52 offset0:64 offset1:80
	ds_write2_b32 v117, v37, v53 offset0:196 offset1:212
	ds_write2_b32 v112, v38, v54 offset0:72 offset1:88
	ds_write2_b32 v112, v39, v55 offset0:204 offset1:220
	ds_write2_b32 v113, v40, v56 offset0:128 offset1:144
	ds_write2_b32 v114, v41, v57 offset0:4 offset1:20
	ds_write2_b32 v114, v42, v58 offset0:136 offset1:152
	ds_write2_b32 v115, v43, v59 offset0:12 offset1:28
	ds_write2_b32 v111, v44, v60 offset0:192 offset1:208
	ds_write2_b32 v118, v45, v61 offset0:68 offset1:84
	ds_write2_b32 v118, v46, v62 offset0:200 offset1:216
	ds_write2_b32 v119, v47, v63 offset0:76 offset1:92
	v_lshl_add_u64 v[36:37], v[140:141], 0, s[56:57]
	s_mov_b32 s37, 0
	v_mov_b32_e32 v40, v135
	s_waitcnt lgkmcnt(0)
	s_barrier
	s_and_b64 vcc, exec, s[48:49]
	s_cbranch_vccnz .Lep1_3_part
	ds_read_b128 v[234:237], v135
	ds_read_b128 v[238:241], v135 offset:8448
	ds_read_b128 v[242:245], v135 offset:16896
	ds_read_b128 v[246:249], v135 offset:25344
	s_waitcnt vmcnt(7) lgkmcnt(3)
	v_pk_fma_f32 v[202:203], v[234:235], v[182:183], v[202:203]
	v_pk_fma_f32 v[204:205], v[236:237], v[184:185], v[204:205]
	global_store_dwordx4 v[186:187], v[202:205], off
	ds_read_b128 v[234:237], v135 offset:33792
	s_waitcnt vmcnt(7) lgkmcnt(3)
	v_pk_fma_f32 v[206:207], v[238:239], v[182:183], v[206:207]
	v_pk_fma_f32 v[208:209], v[240:241], v[184:185], v[208:209]
	global_store_dwordx4 v[188:189], v[206:209], off
	ds_read_b128 v[238:241], v135 offset:42240
	s_waitcnt vmcnt(7) lgkmcnt(3)
	v_pk_fma_f32 v[210:211], v[242:243], v[182:183], v[210:211]
	v_pk_fma_f32 v[212:213], v[244:245], v[184:185], v[212:213]
	global_store_dwordx4 v[190:191], v[210:213], off
	ds_read_b128 v[242:245], v135 offset:50688
	s_waitcnt vmcnt(7) lgkmcnt(3)
	v_pk_fma_f32 v[214:215], v[246:247], v[182:183], v[214:215]
	v_pk_fma_f32 v[216:217], v[248:249], v[184:185], v[216:217]
	global_store_dwordx4 v[192:193], v[214:217], off
	ds_read_b128 v[246:249], v135 offset:59136
	s_waitcnt vmcnt(7) lgkmcnt(3)
	v_pk_fma_f32 v[218:219], v[234:235], v[182:183], v[218:219]
	v_pk_fma_f32 v[220:221], v[236:237], v[184:185], v[220:221]
	global_store_dwordx4 v[194:195], v[218:221], off
	s_waitcnt vmcnt(7) lgkmcnt(2)
	v_pk_fma_f32 v[222:223], v[238:239], v[182:183], v[222:223]
	v_pk_fma_f32 v[224:225], v[240:241], v[184:185], v[224:225]
	global_store_dwordx4 v[196:197], v[222:225], off
	s_waitcnt vmcnt(7) lgkmcnt(1)
	v_pk_fma_f32 v[226:227], v[242:243], v[182:183], v[226:227]
	v_pk_fma_f32 v[228:229], v[244:245], v[184:185], v[228:229]
	global_store_dwordx4 v[198:199], v[226:229], off
	s_waitcnt vmcnt(7) lgkmcnt(0)
	v_pk_fma_f32 v[230:231], v[246:247], v[182:183], v[230:231]
	v_pk_fma_f32 v[232:233], v[248:249], v[184:185], v[232:233]
	global_store_dwordx4 v[200:201], v[230:233], off
	s_branch .Lep1_3_done

.Lep1_3_done:
.LBB0_1150:
	s_and_b64 vcc, exec, s[48:49]
	s_cbranch_vccnz .Lep1_4_skipld
	v_add_u32_e32 v176, 0x80, v110
	v_add_u32_e32 v178, 0xfffff000, v176
	v_lshrrev_b32_e32 v178, 11, v178
	v_mad_u32_u24 v178, v178, s33, s33
	v_cmp_lt_i32_e32 vcc, s94, v176
	v_ashrrev_i32_e32 v177, 31, v176
	v_mov_b32_e32 v179, 0
	v_cndmask_b32_e32 v178, 0, v178, vcc
	v_lshl_add_u64 v[180:181], v[178:179], 2, v[100:101]
	global_load_dwordx4 v[182:185], v[180:181], off offset:512
	v_lshlrev_b64 v[186:187], 13, v[176:177]
	v_lshl_add_u64 v[186:187], v[102:103], 0, v[186:187]
	s_mov_b32 s50, 0x20000
	s_mov_b32 s51, 0
	global_load_dwordx4 v[202:205], v[186:187], off offset:512
	v_lshl_add_u64 v[188:189], v[186:187], 0, s[50:51]
	global_load_dwordx4 v[206:209], v[188:189], off offset:512
	v_lshl_add_u64 v[190:191], v[188:189], 0, s[50:51]
	global_load_dwordx4 v[210:213], v[190:191], off offset:512
	v_lshl_add_u64 v[192:193], v[190:191], 0, s[50:51]
	global_load_dwordx4 v[214:217], v[192:193], off offset:512
	v_lshl_add_u64 v[194:195], v[192:193], 0, s[50:51]
	global_load_dwordx4 v[218:221], v[194:195], off offset:512
	v_lshl_add_u64 v[196:197], v[194:195], 0, s[50:51]
	global_load_dwordx4 v[222:225], v[196:197], off offset:512
	v_lshl_add_u64 v[198:199], v[196:197], 0, s[50:51]
	global_load_dwordx4 v[226:229], v[198:199], off offset:512
	v_lshl_add_u64 v[200:201], v[198:199], 0, s[50:51]
	global_load_dwordx4 v[230:233], v[200:201], off offset:512
.Lep1_4_skipld:
	s_waitcnt lgkmcnt(0)
	s_barrier
	ds_write2_b32 v165, v0, v16 offset1:16
	ds_write2_b32 v165, v1, v17 offset0:132 offset1:148
	ds_write2_b32 v116, v2, v18 offset0:8 offset1:24
	ds_write2_b32 v116, v3, v19 offset0:140 offset1:156
	ds_write2_b32 v117, v4, v20 offset0:64 offset1:80
	ds_write2_b32 v117, v5, v21 offset0:196 offset1:212
	ds_write2_b32 v112, v6, v22 offset0:72 offset1:88
	ds_write2_b32 v112, v7, v23 offset0:204 offset1:220
	ds_write2_b32 v113, v8, v24 offset0:128 offset1:144
	ds_write2_b32 v114, v9, v25 offset0:4 offset1:20
	ds_write2_b32 v114, v10, v26 offset0:136 offset1:152
	ds_write2_b32 v115, v11, v27 offset0:12 offset1:28
	ds_write2_b32 v111, v12, v28 offset0:192 offset1:208
	ds_write2_b32 v118, v13, v29 offset0:68 offset1:84
	ds_write2_b32 v118, v14, v30 offset0:200 offset1:216
	ds_write2_b32 v119, v15, v31 offset0:76 offset1:92
	v_lshl_add_u64 v[4:5], v[142:143], 0, s[56:57]
	s_mov_b32 s37, 0
	v_mov_b32_e32 v8, v135
	s_waitcnt lgkmcnt(0)
	s_barrier
	s_and_b64 vcc, exec, s[48:49]
	s_cbranch_vccnz .Lep1_4_part
	ds_read_b128 v[234:237], v135
	ds_read_b128 v[238:241], v135 offset:8448
	ds_read_b128 v[242:245], v135 offset:16896
	ds_read_b128 v[246:249], v135 offset:25344
	s_waitcnt vmcnt(7) lgkmcnt(3)
	v_pk_fma_f32 v[202:203], v[234:235], v[182:183], v[202:203]
	v_pk_fma_f32 v[204:205], v[236:237], v[184:185], v[204:205]
	global_store_dwordx4 v[186:187], v[202:205], off offset:512
	ds_read_b128 v[234:237], v135 offset:33792
	s_waitcnt vmcnt(7) lgkmcnt(3)
	v_pk_fma_f32 v[206:207], v[238:239], v[182:183], v[206:207]
	v_pk_fma_f32 v[208:209], v[240:241], v[184:185], v[208:209]
	global_store_dwordx4 v[188:189], v[206:209], off offset:512
	ds_read_b128 v[238:241], v135 offset:42240
	s_waitcnt vmcnt(7) lgkmcnt(3)
	v_pk_fma_f32 v[210:211], v[242:243], v[182:183], v[210:211]
	v_pk_fma_f32 v[212:213], v[244:245], v[184:185], v[212:213]
	global_store_dwordx4 v[190:191], v[210:213], off offset:512
	ds_read_b128 v[242:245], v135 offset:50688
	s_waitcnt vmcnt(7) lgkmcnt(3)
	v_pk_fma_f32 v[214:215], v[246:247], v[182:183], v[214:215]
	v_pk_fma_f32 v[216:217], v[248:249], v[184:185], v[216:217]
	global_store_dwordx4 v[192:193], v[214:217], off offset:512
	ds_read_b128 v[246:249], v135 offset:59136
	s_waitcnt vmcnt(7) lgkmcnt(3)
	v_pk_fma_f32 v[218:219], v[234:235], v[182:183], v[218:219]
	v_pk_fma_f32 v[220:221], v[236:237], v[184:185], v[220:221]
	global_store_dwordx4 v[194:195], v[218:221], off offset:512
	s_waitcnt vmcnt(7) lgkmcnt(2)
	v_pk_fma_f32 v[222:223], v[238:239], v[182:183], v[222:223]
	v_pk_fma_f32 v[224:225], v[240:241], v[184:185], v[224:225]
	global_store_dwordx4 v[196:197], v[222:225], off offset:512
	s_waitcnt vmcnt(7) lgkmcnt(1)
	v_pk_fma_f32 v[226:227], v[242:243], v[182:183], v[226:227]
	v_pk_fma_f32 v[228:229], v[244:245], v[184:185], v[228:229]
	global_store_dwordx4 v[198:199], v[226:229], off offset:512
	s_waitcnt vmcnt(7) lgkmcnt(0)
	v_pk_fma_f32 v[230:231], v[246:247], v[182:183], v[230:231]
	v_pk_fma_f32 v[232:233], v[248:249], v[184:185], v[232:233]
	global_store_dwordx4 v[200:201], v[230:233], off offset:512
	s_branch .Lep1_4_done

.LBB0_1374:
	s_and_b64 vcc, exec, s[46:47]
	s_cbranch_vccnz .Lep2_2_skipld
	v_mov_b32_e32 v176, v110
	v_add_u32_e32 v178, 0xfffff000, v176
	v_lshrrev_b32_e32 v178, 11, v178
	v_mad_u32_u24 v178, v178, s33, s33
	v_cmp_lt_i32_e32 vcc, s94, v176
	v_ashrrev_i32_e32 v177, 31, v176
	v_mov_b32_e32 v179, 0
	v_cndmask_b32_e32 v178, 0, v178, vcc
	v_lshl_add_u64 v[180:181], v[178:179], 2, v[100:101]
	global_load_dwordx4 v[182:185], v[180:181], off offset:512
	v_lshlrev_b64 v[186:187], 13, v[176:177]
	v_lshl_add_u64 v[186:187], v[102:103], 0, v[186:187]
	s_mov_b32 s48, 0x20000
	s_mov_b32 s49, 0
	global_load_dwordx4 v[202:205], v[186:187], off offset:512
	v_lshl_add_u64 v[188:189], v[186:187], 0, s[48:49]
	global_load_dwordx4 v[206:209], v[188:189], off offset:512
	v_lshl_add_u64 v[190:191], v[188:189], 0, s[48:49]
	global_load_dwordx4 v[210:213], v[190:191], off offset:512
	v_lshl_add_u64 v[192:193], v[190:191], 0, s[48:49]
	global_load_dwordx4 v[214:217], v[192:193], off offset:512
	v_lshl_add_u64 v[194:195], v[192:193], 0, s[48:49]
	global_load_dwordx4 v[218:221], v[194:195], off offset:512
	v_lshl_add_u64 v[196:197], v[194:195], 0, s[48:49]
	global_load_dwordx4 v[222:225], v[196:197], off offset:512
	v_lshl_add_u64 v[198:199], v[196:197], 0, s[48:49]
	global_load_dwordx4 v[226:229], v[198:199], off offset:512
	v_lshl_add_u64 v[200:201], v[198:199], 0, s[48:49]
	global_load_dwordx4 v[230:233], v[200:201], off offset:512
.Lep2_2_skipld:
	s_waitcnt lgkmcnt(0)
	s_barrier
	ds_write2_b32 v167, v64, v80 offset1:16
	ds_write2_b32 v167, v65, v81 offset0:132 offset1:148
	ds_write2_b32 v116, v66, v82 offset0:8 offset1:24
	ds_write2_b32 v116, v67, v83 offset0:140 offset1:156
	ds_write2_b32 v117, v68, v84 offset0:64 offset1:80
	ds_write2_b32 v117, v69, v85 offset0:196 offset1:212
	ds_write2_b32 v112, v70, v86 offset0:72 offset1:88
	ds_write2_b32 v112, v71, v87 offset0:204 offset1:220
	ds_write2_b32 v113, v72, v88 offset0:128 offset1:144
	ds_write2_b32 v114, v73, v89 offset0:4 offset1:20
	ds_write2_b32 v114, v74, v90 offset0:136 offset1:152
	ds_write2_b32 v115, v75, v91 offset0:12 offset1:28
	ds_write2_b32 v111, v76, v92 offset0:192 offset1:208
	ds_write2_b32 v118, v77, v93 offset0:68 offset1:84
	ds_write2_b32 v118, v78, v94 offset0:200 offset1:216
	ds_write2_b32 v119, v79, v95 offset0:76 offset1:92
	v_or_b32_e32 v64, 0x80, v144
	v_ashrrev_i32_e32 v65, 31, v64
	v_lshlrev_b64 v[64:65], 2, v[64:65]
	v_lshl_add_u64 v[68:69], s[52:53], 0, v[64:65]
	v_lshl_add_u64 v[70:71], s[50:51], 0, v[64:65]
	v_lshl_add_u64 v[72:73], v[138:139], 0, s[4:5]
	s_mov_b32 s56, 0
	v_mov_b32_e32 v78, v135
	s_waitcnt lgkmcnt(0)
	s_barrier
	s_and_b64 vcc, exec, s[46:47]
	s_cbranch_vccnz .Lep2_2_part
	ds_read_b128 v[234:237], v135
	ds_read_b128 v[238:241], v135 offset:8448
	ds_read_b128 v[242:245], v135 offset:16896
	ds_read_b128 v[246:249], v135 offset:25344
	s_waitcnt vmcnt(7) lgkmcnt(3)
	v_pk_fma_f32 v[202:203], v[234:235], v[182:183], v[202:203]
	v_pk_fma_f32 v[204:205], v[236:237], v[184:185], v[204:205]
	global_store_dwordx4 v[186:187], v[202:205], off offset:512
	ds_read_b128 v[234:237], v135 offset:33792
	s_waitcnt vmcnt(7) lgkmcnt(3)
	v_pk_fma_f32 v[206:207], v[238:239], v[182:183], v[206:207]
	v_pk_fma_f32 v[208:209], v[240:241], v[184:185], v[208:209]
	global_store_dwordx4 v[188:189], v[206:209], off offset:512
	ds_read_b128 v[238:241], v135 offset:42240
	s_waitcnt vmcnt(7) lgkmcnt(3)
	v_pk_fma_f32 v[210:211], v[242:243], v[182:183], v[210:211]
	v_pk_fma_f32 v[212:213], v[244:245], v[184:185], v[212:213]
	global_store_dwordx4 v[190:191], v[210:213], off offset:512
	ds_read_b128 v[242:245], v135 offset:50688
	s_waitcnt vmcnt(7) lgkmcnt(3)
	v_pk_fma_f32 v[214:215], v[246:247], v[182:183], v[214:215]
	v_pk_fma_f32 v[216:217], v[248:249], v[184:185], v[216:217]
	global_store_dwordx4 v[192:193], v[214:217], off offset:512
	ds_read_b128 v[246:249], v135 offset:59136
	s_waitcnt vmcnt(7) lgkmcnt(3)
	v_pk_fma_f32 v[218:219], v[234:235], v[182:183], v[218:219]
	v_pk_fma_f32 v[220:221], v[236:237], v[184:185], v[220:221]
	global_store_dwordx4 v[194:195], v[218:221], off offset:512
	s_waitcnt vmcnt(7) lgkmcnt(2)
	v_pk_fma_f32 v[222:223], v[238:239], v[182:183], v[222:223]
	v_pk_fma_f32 v[224:225], v[240:241], v[184:185], v[224:225]
	global_store_dwordx4 v[196:197], v[222:225], off offset:512
	s_waitcnt vmcnt(7) lgkmcnt(1)
	v_pk_fma_f32 v[226:227], v[242:243], v[182:183], v[226:227]
	v_pk_fma_f32 v[228:229], v[244:245], v[184:185], v[228:229]
	global_store_dwordx4 v[198:199], v[226:229], off offset:512
	s_waitcnt vmcnt(7) lgkmcnt(0)
	v_pk_fma_f32 v[230:231], v[246:247], v[182:183], v[230:231]
	v_pk_fma_f32 v[232:233], v[248:249], v[184:185], v[232:233]
	global_store_dwordx4 v[200:201], v[230:233], off offset:512
	s_branch .Lep2_2_done

.Lep2_2_done:
.LBB0_1384:
	s_and_b64 vcc, exec, s[46:47]
	s_cbranch_vccnz .Lep2_3_skipld
	v_add_u32_e32 v176, 0x80, v110
	v_add_u32_e32 v178, 0xfffff000, v176
	v_lshrrev_b32_e32 v178, 11, v178
	v_mad_u32_u24 v178, v178, s33, s33
	v_cmp_lt_i32_e32 vcc, s94, v176
	v_ashrrev_i32_e32 v177, 31, v176
	v_mov_b32_e32 v179, 0
	v_cndmask_b32_e32 v178, 0, v178, vcc
	v_lshl_add_u64 v[180:181], v[178:179], 2, v[100:101]
	global_load_dwordx4 v[182:185], v[180:181], off
	v_lshlrev_b64 v[186:187], 13, v[176:177]
	v_lshl_add_u64 v[186:187], v[102:103], 0, v[186:187]
	s_mov_b32 s48, 0x20000
	s_mov_b32 s49, 0
	global_load_dwordx4 v[202:205], v[186:187], off
	v_lshl_add_u64 v[188:189], v[186:187], 0, s[48:49]
	global_load_dwordx4 v[206:209], v[188:189], off
	v_lshl_add_u64 v[190:191], v[188:189], 0, s[48:49]
	global_load_dwordx4 v[210:213], v[190:191], off
	v_lshl_add_u64 v[192:193], v[190:191], 0, s[48:49]
	global_load_dwordx4 v[214:217], v[192:193], off
	v_lshl_add_u64 v[194:195], v[192:193], 0, s[48:49]
	global_load_dwordx4 v[218:221], v[194:195], off
	v_lshl_add_u64 v[196:197], v[194:195], 0, s[48:49]
	global_load_dwordx4 v[222:225], v[196:197], off
	v_lshl_add_u64 v[198:199], v[196:197], 0, s[48:49]
	global_load_dwordx4 v[226:229], v[198:199], off
	v_lshl_add_u64 v[200:201], v[198:199], 0, s[48:49]
	global_load_dwordx4 v[230:233], v[200:201], off
.Lep2_3_skipld:
	s_waitcnt lgkmcnt(0)
	s_barrier
	ds_write2_b32 v167, v32, v48 offset1:16
	ds_write2_b32 v167, v33, v49 offset0:132 offset1:148
	ds_write2_b32 v116, v34, v50 offset0:8 offset1:24
	ds_write2_b32 v116, v35, v51 offset0:140 offset1:156
	ds_write2_b32 v117, v36, v52 offset0:64 offset1:80
	ds_write2_b32 v117, v37, v53 offset0:196 offset1:212
	ds_write2_b32 v112, v38, v54 offset0:72 offset1:88
	ds_write2_b32 v112, v39, v55 offset0:204 offset1:220
	ds_write2_b32 v113, v40, v56 offset0:128 offset1:144
	ds_write2_b32 v114, v41, v57 offset0:4 offset1:20
	ds_write2_b32 v114, v42, v58 offset0:136 offset1:152
	ds_write2_b32 v115, v43, v59 offset0:12 offset1:28
	ds_write2_b32 v111, v44, v60 offset0:192 offset1:208
	ds_write2_b32 v118, v45, v61 offset0:68 offset1:84
	ds_write2_b32 v118, v46, v62 offset0:200 offset1:216
	ds_write2_b32 v119, v47, v63 offset0:76 offset1:92
	v_lshl_add_u64 v[36:37], v[140:141], 0, s[4:5]
	s_mov_b32 s54, 0
	v_mov_b32_e32 v40, v135
	s_waitcnt lgkmcnt(0)
	s_barrier
	s_and_b64 vcc, exec, s[46:47]
	s_cbranch_vccnz .Lep2_3_part
	ds_read_b128 v[234:237], v135
	ds_read_b128 v[238:241], v135 offset:8448
	ds_read_b128 v[242:245], v135 offset:16896
	ds_read_b128 v[246:249], v135 offset:25344
	s_waitcnt vmcnt(7) lgkmcnt(3)
	v_pk_fma_f32 v[202:203], v[234:235], v[182:183], v[202:203]
	v_pk_fma_f32 v[204:205], v[236:237], v[184:185], v[204:205]
	global_store_dwordx4 v[186:187], v[202:205], off
	ds_read_b128 v[234:237], v135 offset:33792
	s_waitcnt vmcnt(7) lgkmcnt(3)
	v_pk_fma_f32 v[206:207], v[238:239], v[182:183], v[206:207]
	v_pk_fma_f32 v[208:209], v[240:241], v[184:185], v[208:209]
	global_store_dwordx4 v[188:189], v[206:209], off
	ds_read_b128 v[238:241], v135 offset:42240
	s_waitcnt vmcnt(7) lgkmcnt(3)
	v_pk_fma_f32 v[210:211], v[242:243], v[182:183], v[210:211]
	v_pk_fma_f32 v[212:213], v[244:245], v[184:185], v[212:213]
	global_store_dwordx4 v[190:191], v[210:213], off
	ds_read_b128 v[242:245], v135 offset:50688
	s_waitcnt vmcnt(7) lgkmcnt(3)
	v_pk_fma_f32 v[214:215], v[246:247], v[182:183], v[214:215]
	v_pk_fma_f32 v[216:217], v[248:249], v[184:185], v[216:217]
	global_store_dwordx4 v[192:193], v[214:217], off
	ds_read_b128 v[246:249], v135 offset:59136
	s_waitcnt vmcnt(7) lgkmcnt(3)
	v_pk_fma_f32 v[218:219], v[234:235], v[182:183], v[218:219]
	v_pk_fma_f32 v[220:221], v[236:237], v[184:185], v[220:221]
	global_store_dwordx4 v[194:195], v[218:221], off
	s_waitcnt vmcnt(7) lgkmcnt(2)
	v_pk_fma_f32 v[222:223], v[238:239], v[182:183], v[222:223]
	v_pk_fma_f32 v[224:225], v[240:241], v[184:185], v[224:225]
	global_store_dwordx4 v[196:197], v[222:225], off
	s_waitcnt vmcnt(7) lgkmcnt(1)
	v_pk_fma_f32 v[226:227], v[242:243], v[182:183], v[226:227]
	v_pk_fma_f32 v[228:229], v[244:245], v[184:185], v[228:229]
	global_store_dwordx4 v[198:199], v[226:229], off
	s_waitcnt vmcnt(7) lgkmcnt(0)
	v_pk_fma_f32 v[230:231], v[246:247], v[182:183], v[230:231]
	v_pk_fma_f32 v[232:233], v[248:249], v[184:185], v[232:233]
	global_store_dwordx4 v[200:201], v[230:233], off
	s_branch .Lep2_3_done

.Lep2_3_done:
.LBB0_1394:
	s_and_b64 vcc, exec, s[46:47]
	s_cbranch_vccnz .Lep2_4_skipld
	v_add_u32_e32 v176, 0x80, v110
	v_add_u32_e32 v178, 0xfffff000, v176
	v_lshrrev_b32_e32 v178, 11, v178
	v_mad_u32_u24 v178, v178, s33, s33
	v_cmp_lt_i32_e32 vcc, s94, v176
	v_ashrrev_i32_e32 v177, 31, v176
	v_mov_b32_e32 v179, 0
	v_cndmask_b32_e32 v178, 0, v178, vcc
	v_lshl_add_u64 v[180:181], v[178:179], 2, v[100:101]
	global_load_dwordx4 v[182:185], v[180:181], off offset:512
	v_lshlrev_b64 v[186:187], 13, v[176:177]
	v_lshl_add_u64 v[186:187], v[102:103], 0, v[186:187]
	s_mov_b32 s48, 0x20000
	s_mov_b32 s49, 0
	global_load_dwordx4 v[202:205], v[186:187], off offset:512
	v_lshl_add_u64 v[188:189], v[186:187], 0, s[48:49]
	global_load_dwordx4 v[206:209], v[188:189], off offset:512
	v_lshl_add_u64 v[190:191], v[188:189], 0, s[48:49]
	global_load_dwordx4 v[210:213], v[190:191], off offset:512
	v_lshl_add_u64 v[192:193], v[190:191], 0, s[48:49]
	global_load_dwordx4 v[214:217], v[192:193], off offset:512
	v_lshl_add_u64 v[194:195], v[192:193], 0, s[48:49]
	global_load_dwordx4 v[218:221], v[194:195], off offset:512
	v_lshl_add_u64 v[196:197], v[194:195], 0, s[48:49]
	global_load_dwordx4 v[222:225], v[196:197], off offset:512
	v_lshl_add_u64 v[198:199], v[196:197], 0, s[48:49]
	global_load_dwordx4 v[226:229], v[198:199], off offset:512
	v_lshl_add_u64 v[200:201], v[198:199], 0, s[48:49]
	global_load_dwordx4 v[230:233], v[200:201], off offset:512
.Lep2_4_skipld:
	s_waitcnt lgkmcnt(0)
	s_barrier
	ds_write2_b32 v167, v0, v16 offset1:16
	ds_write2_b32 v167, v1, v17 offset0:132 offset1:148
	ds_write2_b32 v116, v2, v18 offset0:8 offset1:24
	ds_write2_b32 v116, v3, v19 offset0:140 offset1:156
	ds_write2_b32 v117, v4, v20 offset0:64 offset1:80
	ds_write2_b32 v117, v5, v21 offset0:196 offset1:212
	ds_write2_b32 v112, v6, v22 offset0:72 offset1:88
	ds_write2_b32 v112, v7, v23 offset0:204 offset1:220
	ds_write2_b32 v113, v8, v24 offset0:128 offset1:144
	ds_write2_b32 v114, v9, v25 offset0:4 offset1:20
	ds_write2_b32 v114, v10, v26 offset0:136 offset1:152
	ds_write2_b32 v115, v11, v27 offset0:12 offset1:28
	ds_write2_b32 v111, v12, v28 offset0:192 offset1:208
	ds_write2_b32 v118, v13, v29 offset0:68 offset1:84
	ds_write2_b32 v118, v14, v30 offset0:200 offset1:216
	ds_write2_b32 v119, v15, v31 offset0:76 offset1:92
	v_lshl_add_u64 v[4:5], v[142:143], 0, s[4:5]
	s_mov_b32 s48, 0
	v_mov_b32_e32 v8, v135
	s_waitcnt lgkmcnt(0)
	s_barrier
	s_and_b64 vcc, exec, s[46:47]
	s_cbranch_vccnz .Lep2_4_part
	ds_read_b128 v[234:237], v135
	ds_read_b128 v[238:241], v135 offset:8448
	ds_read_b128 v[242:245], v135 offset:16896
	ds_read_b128 v[246:249], v135 offset:25344
	s_waitcnt vmcnt(7) lgkmcnt(3)
	v_pk_fma_f32 v[202:203], v[234:235], v[182:183], v[202:203]
	v_pk_fma_f32 v[204:205], v[236:237], v[184:185], v[204:205]
	global_store_dwordx4 v[186:187], v[202:205], off offset:512
	ds_read_b128 v[234:237], v135 offset:33792
	s_waitcnt vmcnt(7) lgkmcnt(3)
	v_pk_fma_f32 v[206:207], v[238:239], v[182:183], v[206:207]
	v_pk_fma_f32 v[208:209], v[240:241], v[184:185], v[208:209]
	global_store_dwordx4 v[188:189], v[206:209], off offset:512
	ds_read_b128 v[238:241], v135 offset:42240
	s_waitcnt vmcnt(7) lgkmcnt(3)
	v_pk_fma_f32 v[210:211], v[242:243], v[182:183], v[210:211]
	v_pk_fma_f32 v[212:213], v[244:245], v[184:185], v[212:213]
	global_store_dwordx4 v[190:191], v[210:213], off offset:512
	ds_read_b128 v[242:245], v135 offset:50688
	s_waitcnt vmcnt(7) lgkmcnt(3)
	v_pk_fma_f32 v[214:215], v[246:247], v[182:183], v[214:215]
	v_pk_fma_f32 v[216:217], v[248:249], v[184:185], v[216:217]
	global_store_dwordx4 v[192:193], v[214:217], off offset:512
	ds_read_b128 v[246:249], v135 offset:59136
	s_waitcnt vmcnt(7) lgkmcnt(3)
	v_pk_fma_f32 v[218:219], v[234:235], v[182:183], v[218:219]
	v_pk_fma_f32 v[220:221], v[236:237], v[184:185], v[220:221]
	global_store_dwordx4 v[194:195], v[218:221], off offset:512
	s_waitcnt vmcnt(7) lgkmcnt(2)
	v_pk_fma_f32 v[222:223], v[238:239], v[182:183], v[222:223]
	v_pk_fma_f32 v[224:225], v[240:241], v[184:185], v[224:225]
	global_store_dwordx4 v[196:197], v[222:225], off offset:512
	s_waitcnt vmcnt(7) lgkmcnt(1)
	v_pk_fma_f32 v[226:227], v[242:243], v[182:183], v[226:227]
	v_pk_fma_f32 v[228:229], v[244:245], v[184:185], v[228:229]
	global_store_dwordx4 v[198:199], v[226:229], off offset:512
	s_waitcnt vmcnt(7) lgkmcnt(0)
	v_pk_fma_f32 v[230:231], v[246:247], v[182:183], v[230:231]
	v_pk_fma_f32 v[232:233], v[248:249], v[184:185], v[232:233]
	global_store_dwordx4 v[200:201], v[230:233], off offset:512
	s_branch .Lep2_4_done
